# dma2: stack4 + attention steady loop: LDS-DMA burst at the QK/PV boundary spread (1 stays, 1 each in PV gaps 1 and 2), address temps in free VGPRs
# speedup vs baseline: 1.0076x; 1.0076x over previous
.LBB0_413:
	s_mov_b32 s16, s26
	s_mov_b32 s2, s18
	s_mov_b32 s3, s24
	v_lshl_add_u32 v69, s17, 1, v232
	ds_read_b64_tr_b16 v[76:77], v69 offset:24576
	ds_read_b64_tr_b16 v[78:79], v69 offset:25088
	v_add_f32_e32 v72, v100, v101
	v_add_f32_e32 v72, v102, v72
	v_add_f32_e32 v72, v103, v72
	v_add_f32_e32 v72, v104, v72
	v_add_f32_e32 v72, v105, v72
	v_cvt_pk_bf16_f32 v160, v100, v101
	v_cvt_pk_bf16_f32 v161, v102, v103
	s_waitcnt lgkmcnt(9)
	v_mfma_f32_32x32x16_bf16 v[132:147], v[208:211], v[176:179], 0
	v_add_f32_e32 v72, v106, v72
	v_add_f32_e32 v72, v107, v72
	v_add_f32_e32 v72, v108, v72
	v_add_f32_e32 v72, v109, v72
	v_cvt_pk_bf16_f32 v162, v104, v105
	v_cvt_pk_bf16_f32 v163, v106, v107
	s_waitcnt lgkmcnt(8)
	v_mfma_f32_32x32x16_bf16 v[116:131], v[200:203], v[176:179], 0
	ds_read_b64_tr_b16 v[80:81], v69 offset:25600
	ds_read_b64_tr_b16 v[82:83], v69 offset:26112
	v_add_f32_e32 v72, v110, v72
	v_add_f32_e32 v72, v111, v72
	v_add_f32_e32 v72, v112, v72
	v_add_f32_e32 v72, v113, v72
	v_cvt_pk_bf16_f32 v156, v108, v109
	v_cvt_pk_bf16_f32 v157, v110, v111
	s_waitcnt lgkmcnt(9)
	v_mfma_f32_32x32x16_bf16 v[132:147], v[204:207], v[172:175], v[132:147]
	v_add_f32_e32 v72, v114, v72
	v_add_f32_e32 v72, v115, v72
	v_add_f32_e32 v72, v84, v72
	v_add_f32_e32 v72, v85, v72
	v_cvt_pk_bf16_f32 v158, v112, v113
	v_cvt_pk_bf16_f32 v159, v114, v115
	s_waitcnt lgkmcnt(8)
	v_mfma_f32_32x32x16_bf16 v[116:131], v[196:199], v[172:175], v[116:131]
	ds_read_b64_tr_b16 v[100:101], v69 offset:26624
	ds_read_b64_tr_b16 v[102:103], v69 offset:27136
	v_add_f32_e32 v72, v86, v72
	v_add_f32_e32 v72, v87, v72
	v_add_f32_e32 v72, v88, v72
	v_add_f32_e32 v72, v89, v72
	v_cvt_pk_bf16_f32 v152, v84, v85
	v_cvt_pk_bf16_f32 v153, v86, v87
	s_waitcnt lgkmcnt(9)
	v_mfma_f32_32x32x16_bf16 v[132:147], v[192:195], v[168:171], v[132:147]
	v_add_f32_e32 v72, v90, v72
	v_add_f32_e32 v72, v91, v72
	v_add_f32_e32 v72, v92, v72
	v_add_f32_e32 v72, v93, v72
	v_cvt_pk_bf16_f32 v154, v88, v89
	v_cvt_pk_bf16_f32 v155, v90, v91
	s_waitcnt lgkmcnt(8)
	v_mfma_f32_32x32x16_bf16 v[116:131], v[188:191], v[168:171], v[116:131]
	ds_read_b64_tr_b16 v[84:85], v69 offset:27648
	ds_read_b64_tr_b16 v[86:87], v69 offset:28160
	v_add_f32_e32 v72, v94, v72
	v_add_f32_e32 v72, v95, v72
	v_add_f32_e32 v72, v96, v72
	v_add_f32_e32 v72, v97, v72
	v_cvt_pk_bf16_f32 v148, v92, v93
	v_cvt_pk_bf16_f32 v149, v94, v95
	s_waitcnt lgkmcnt(9)
	v_mfma_f32_32x32x16_bf16 v[132:147], v[184:187], v[164:167], v[132:147]
	v_add_f32_e32 v72, v98, v72
	v_add_f32_e32 v72, v99, v72
	v_add_f32_e32 v72, 0, v72
	v_cvt_pk_bf16_f32 v150, v96, v97
	v_cvt_pk_bf16_f32 v151, v98, v99
	s_waitcnt lgkmcnt(8)
	v_mfma_f32_32x32x16_bf16 v[116:131], v[180:183], v[164:167], v[116:131]
	v_lshl_add_u64 v[248:249], v[0:1], 0, s[14:15]
	v_add_f32_e32 v68, v68, v72
	s_add_i32 m0, s24, s0
	v_lshl_add_u64 v[250:251], v[248:249], 0, s[76:77]
	global_load_lds_dwordx4 v[250:251], off
	s_lshl_b32 s17, s26, 1
	s_add_i32 s17, s17, s1
	v_lshl_add_u64 v[254:255], v[70:71], 0, s[14:15]
	s_waitcnt lgkmcnt(6)
	v_mfma_f32_32x32x16_bf16 v[36:51], v[160:163], v[76:79], v[36:51]
	v_exp_f32_e32 v132, v132
	v_exp_f32_e32 v133, v133
	s_mov_b32 m0, s17
	v_lshl_add_u64 v[252:253], v[254:255], 0, s[90:91]
	global_load_lds_dwordx4 v[252:253], off
	ds_read_b64_tr_b16 v[76:77], v69 offset:28672
	ds_read_b64_tr_b16 v[78:79], v69 offset:29184
	s_waitcnt lgkmcnt(6)
	v_mfma_f32_32x32x16_bf16 v[36:51], v[156:159], v[80:83], v[36:51]
	v_exp_f32_e32 v134, v134
	v_exp_f32_e32 v135, v135
	s_add_i32 m0, s17, 0x2000
	v_lshl_add_u64 v[250:251], v[254:255], 0, s[92:93]
	global_load_lds_dwordx4 v[250:251], off
	ds_read_b64_tr_b16 v[80:81], v69 offset:29696
	ds_read_b64_tr_b16 v[82:83], v69 offset:30208
	s_waitcnt lgkmcnt(6)
	v_mfma_f32_32x32x16_bf16 v[36:51], v[152:155], v[100:103], v[36:51]
	v_exp_f32_e32 v136, v136
	v_exp_f32_e32 v137, v137
	ds_read_b64_tr_b16 v[88:89], v69 offset:30720
	ds_read_b64_tr_b16 v[90:91], v69 offset:31232
	s_waitcnt lgkmcnt(6)
	v_mfma_f32_32x32x16_bf16 v[36:51], v[148:151], v[84:87], v[36:51]
	v_exp_f32_e32 v138, v138
	v_exp_f32_e32 v139, v139
	ds_read_b64_tr_b16 v[84:85], v69 offset:31744
	ds_read_b64_tr_b16 v[86:87], v69 offset:32256
	s_waitcnt lgkmcnt(6)
	v_mfma_f32_32x32x16_bf16 v[52:67], v[160:163], v[76:79], v[52:67]
	v_exp_f32_e32 v140, v140
	v_exp_f32_e32 v141, v141
	ds_read_b64_tr_b16 v[76:77], v69 offset:32768
	ds_read_b64_tr_b16 v[78:79], v69 offset:33280
	s_waitcnt lgkmcnt(6)
	v_mfma_f32_32x32x16_bf16 v[52:67], v[156:159], v[80:83], v[52:67]
	v_exp_f32_e32 v142, v142
	v_exp_f32_e32 v143, v143
	ds_read_b64_tr_b16 v[80:81], v69 offset:33792
	ds_read_b64_tr_b16 v[82:83], v69 offset:34304
	s_waitcnt lgkmcnt(6)
	v_mfma_f32_32x32x16_bf16 v[52:67], v[152:155], v[88:91], v[52:67]
	v_exp_f32_e32 v144, v144
	v_exp_f32_e32 v145, v145
	ds_read_b64_tr_b16 v[88:89], v69 offset:34816
	ds_read_b64_tr_b16 v[90:91], v69 offset:35328
	s_waitcnt lgkmcnt(6)
	v_mfma_f32_32x32x16_bf16 v[52:67], v[148:151], v[84:87], v[52:67]
	v_exp_f32_e32 v146, v146
	v_exp_f32_e32 v147, v147
	ds_read_b64_tr_b16 v[84:85], v69 offset:35840
	ds_read_b64_tr_b16 v[86:87], v69 offset:36352
	s_waitcnt lgkmcnt(6)
	v_mfma_f32_32x32x16_bf16 v[4:19], v[160:163], v[76:79], v[4:19]
	v_exp_f32_e32 v116, v116
	v_exp_f32_e32 v117, v117
	ds_read_b64_tr_b16 v[76:77], v69 offset:36864
	ds_read_b64_tr_b16 v[78:79], v69 offset:37376
	s_waitcnt lgkmcnt(6)
	v_mfma_f32_32x32x16_bf16 v[4:19], v[156:159], v[80:83], v[4:19]
	v_exp_f32_e32 v118, v118
	v_exp_f32_e32 v119, v119
	ds_read_b64_tr_b16 v[80:81], v69 offset:37888
	ds_read_b64_tr_b16 v[82:83], v69 offset:38400
	s_waitcnt lgkmcnt(6)
	v_mfma_f32_32x32x16_bf16 v[4:19], v[152:155], v[88:91], v[4:19]
	v_exp_f32_e32 v120, v120
	v_exp_f32_e32 v121, v121
	ds_read_b64_tr_b16 v[88:89], v69 offset:38912
	ds_read_b64_tr_b16 v[90:91], v69 offset:39424
	s_waitcnt lgkmcnt(6)
	v_mfma_f32_32x32x16_bf16 v[4:19], v[148:151], v[84:87], v[4:19]
	v_exp_f32_e32 v122, v122
	v_exp_f32_e32 v123, v123
	ds_read_b64_tr_b16 v[84:85], v69 offset:39936
	ds_read_b64_tr_b16 v[86:87], v69 offset:40448
	v_add_u32_e32 v69, s16, v230
	ds_read_b128 v[92:95], v69
	ds_read_b128 v[96:99], v69 offset:512
	s_waitcnt lgkmcnt(8)
	v_mfma_f32_32x32x16_bf16 v[20:35], v[160:163], v[76:79], v[20:35]
	v_exp_f32_e32 v124, v124
	v_exp_f32_e32 v125, v125
	ds_read_b128 v[76:79], v69 offset:2048
	ds_read_b128 v[180:183], v69 offset:2560
	s_waitcnt lgkmcnt(8)
	v_mfma_f32_32x32x16_bf16 v[20:35], v[156:159], v[80:83], v[20:35]
	v_exp_f32_e32 v126, v126
	v_exp_f32_e32 v127, v127
	ds_read_b128 v[80:83], v69 offset:4096
	ds_read_b128 v[184:187], v69 offset:4608
	ds_read_b128 v[188:191], v69 offset:6144
	ds_read_b128 v[192:195], v69 offset:6656
	s_waitcnt lgkmcnt(10)
	v_mfma_f32_32x32x16_bf16 v[20:35], v[152:155], v[88:91], v[20:35]
	v_exp_f32_e32 v128, v128
	v_exp_f32_e32 v129, v129
	s_waitcnt lgkmcnt(8)
	v_mfma_f32_32x32x16_bf16 v[20:35], v[148:151], v[84:87], v[20:35]
	v_exp_f32_e32 v130, v130
	v_exp_f32_e32 v131, v131
	s_add_i32 s17, s26, 0x2000
	s_cmpk_lg_i32 s26, 0x4000
	s_cselect_b32 s24, s17, 0
	v_lshl_add_u32 v69, s3, 1, v232
	s_waitcnt vmcnt(3) lgkmcnt(0)
	s_barrier
	ds_read_b64_tr_b16 v[196:197], v69 offset:24576
	ds_read_b64_tr_b16 v[198:199], v69 offset:25088
	s_waitcnt lgkmcnt(9)
	v_mfma_f32_32x32x16_bf16 v[100:115], v[92:95], v[176:179], 0
	v_add_f32_e32 v84, v132, v133
	v_add_f32_e32 v84, v134, v84
	v_add_f32_e32 v84, v135, v84
	v_add_f32_e32 v84, v136, v84
	v_add_f32_e32 v84, v137, v84
	v_cvt_pk_bf16_f32 v160, v132, v133
	v_cvt_pk_bf16_f32 v161, v134, v135
	v_add_f32_e32 v84, v138, v84
	v_add_f32_e32 v84, v139, v84
	v_add_f32_e32 v84, v140, v84
	v_add_f32_e32 v148, v141, v84
	s_waitcnt lgkmcnt(8)
	v_mfma_f32_32x32x16_bf16 v[84:99], v[96:99], v[176:179], 0
	v_cvt_pk_bf16_f32 v162, v136, v137
	v_cvt_pk_bf16_f32 v163, v138, v139
	ds_read_b64_tr_b16 v[132:133], v69 offset:25600
	ds_read_b64_tr_b16 v[134:135], v69 offset:26112
	s_waitcnt lgkmcnt(9)
	v_mfma_f32_32x32x16_bf16 v[100:115], v[76:79], v[172:175], v[100:115]
	v_add_f32_e32 v76, v142, v148
	v_add_f32_e32 v76, v143, v76
	v_add_f32_e32 v76, v144, v76
	v_add_f32_e32 v76, v145, v76
	v_cvt_pk_bf16_f32 v156, v140, v141
	v_cvt_pk_bf16_f32 v157, v142, v143
	s_waitcnt lgkmcnt(8)
	v_mfma_f32_32x32x16_bf16 v[84:99], v[180:183], v[172:175], v[84:99]
	v_add_f32_e32 v76, v146, v76
	v_add_f32_e32 v76, v147, v76
	v_add_f32_e32 v76, v116, v76
	v_add_f32_e32 v136, v117, v76
	v_cvt_pk_bf16_f32 v158, v144, v145
	v_cvt_pk_bf16_f32 v159, v146, v147
	ds_read_b64_tr_b16 v[76:77], v69 offset:26624
	ds_read_b64_tr_b16 v[78:79], v69 offset:27136
	s_waitcnt lgkmcnt(9)
	v_mfma_f32_32x32x16_bf16 v[100:115], v[80:83], v[168:171], v[100:115]
	v_add_f32_e32 v80, v118, v136
	v_add_f32_e32 v80, v119, v80
	v_add_f32_e32 v80, v120, v80
	v_add_f32_e32 v80, v121, v80
	v_cvt_pk_bf16_f32 v152, v116, v117
	v_cvt_pk_bf16_f32 v153, v118, v119
	s_waitcnt lgkmcnt(8)
	v_mfma_f32_32x32x16_bf16 v[84:99], v[184:187], v[168:171], v[84:99]
	v_add_f32_e32 v80, v122, v80
	v_add_f32_e32 v80, v123, v80
	v_add_f32_e32 v80, v124, v80
	v_add_f32_e32 v116, v125, v80
	v_cvt_pk_bf16_f32 v154, v120, v121
	v_cvt_pk_bf16_f32 v155, v122, v123
	ds_read_b64_tr_b16 v[80:81], v69 offset:27648
	ds_read_b64_tr_b16 v[82:83], v69 offset:28160
	s_waitcnt lgkmcnt(9)
	v_mfma_f32_32x32x16_bf16 v[100:115], v[188:191], v[164:167], v[100:115]
	v_add_f32_e32 v116, v126, v116
	v_add_f32_e32 v116, v127, v116
	v_add_f32_e32 v116, v128, v116
	v_add_f32_e32 v116, v129, v116
	v_cvt_pk_bf16_f32 v148, v124, v125
	v_cvt_pk_bf16_f32 v149, v126, v127
	s_waitcnt lgkmcnt(8)
	v_mfma_f32_32x32x16_bf16 v[84:99], v[192:195], v[164:167], v[84:99]
	v_add_f32_e32 v116, v130, v116
	v_add_f32_e32 v116, v131, v116
	v_add_f32_e32 v116, 0, v116
	v_cvt_pk_bf16_f32 v150, v128, v129
	v_cvt_pk_bf16_f32 v151, v130, v131
	s_add_i32 m0, s26, s0
	v_lshl_add_u64 v[250:251], v[248:249], 0, s[28:29]
	global_load_lds_dwordx4 v[250:251], off
	s_lshl_b32 s3, s24, 1
	s_add_i32 s3, s3, s1
	v_add_f32_e32 v68, v68, v116
	s_waitcnt lgkmcnt(6)
	v_mfma_f32_32x32x16_bf16 v[36:51], v[160:163], v[196:199], v[36:51]
	v_exp_f32_e32 v100, v100
	v_exp_f32_e32 v101, v101
	s_mov_b32 m0, s3
	v_lshl_add_u64 v[252:253], v[254:255], 0, s[66:67]
	global_load_lds_dwordx4 v[252:253], off
	ds_read_b64_tr_b16 v[72:73], v69 offset:28672
	ds_read_b64_tr_b16 v[74:75], v69 offset:29184
	s_waitcnt lgkmcnt(6)
	v_mfma_f32_32x32x16_bf16 v[36:51], v[156:159], v[132:135], v[36:51]
	v_exp_f32_e32 v102, v102
	v_exp_f32_e32 v103, v103
	s_add_i32 m0, s3, 0x2000
	v_lshl_add_u64 v[250:251], v[254:255], 0, s[72:73]
	global_load_lds_dwordx4 v[250:251], off
	ds_read_b64_tr_b16 v[116:117], v69 offset:29696
	ds_read_b64_tr_b16 v[118:119], v69 offset:30208
	s_waitcnt lgkmcnt(6)
	v_mfma_f32_32x32x16_bf16 v[36:51], v[152:155], v[76:79], v[36:51]
	v_exp_f32_e32 v104, v104
	v_exp_f32_e32 v105, v105
	ds_read_b64_tr_b16 v[76:77], v69 offset:30720
	ds_read_b64_tr_b16 v[78:79], v69 offset:31232
	s_waitcnt lgkmcnt(6)
	v_mfma_f32_32x32x16_bf16 v[36:51], v[148:151], v[80:83], v[36:51]
	v_exp_f32_e32 v106, v106
	v_exp_f32_e32 v107, v107
	ds_read_b64_tr_b16 v[80:81], v69 offset:31744
	ds_read_b64_tr_b16 v[82:83], v69 offset:32256
	s_waitcnt lgkmcnt(6)
	v_mfma_f32_32x32x16_bf16 v[52:67], v[160:163], v[72:75], v[52:67]
	v_exp_f32_e32 v108, v108
	v_exp_f32_e32 v109, v109
	ds_read_b64_tr_b16 v[72:73], v69 offset:32768
	ds_read_b64_tr_b16 v[74:75], v69 offset:33280
	s_waitcnt lgkmcnt(6)
	v_mfma_f32_32x32x16_bf16 v[52:67], v[156:159], v[116:119], v[52:67]
	v_exp_f32_e32 v110, v110
	v_exp_f32_e32 v111, v111
	ds_read_b64_tr_b16 v[116:117], v69 offset:33792
	ds_read_b64_tr_b16 v[118:119], v69 offset:34304
	s_waitcnt lgkmcnt(6)
	v_mfma_f32_32x32x16_bf16 v[52:67], v[152:155], v[76:79], v[52:67]
	v_exp_f32_e32 v112, v112
	v_exp_f32_e32 v113, v113
	ds_read_b64_tr_b16 v[76:77], v69 offset:34816
	ds_read_b64_tr_b16 v[78:79], v69 offset:35328
	s_waitcnt lgkmcnt(6)
	v_mfma_f32_32x32x16_bf16 v[52:67], v[148:151], v[80:83], v[52:67]
	v_exp_f32_e32 v114, v114
	v_exp_f32_e32 v115, v115
	ds_read_b64_tr_b16 v[80:81], v69 offset:35840
	ds_read_b64_tr_b16 v[82:83], v69 offset:36352
	s_waitcnt lgkmcnt(6)
	v_mfma_f32_32x32x16_bf16 v[4:19], v[160:163], v[72:75], v[4:19]
	v_exp_f32_e32 v84, v84
	v_exp_f32_e32 v85, v85
	ds_read_b64_tr_b16 v[72:73], v69 offset:36864
	ds_read_b64_tr_b16 v[74:75], v69 offset:37376
	s_waitcnt lgkmcnt(6)
	v_mfma_f32_32x32x16_bf16 v[4:19], v[156:159], v[116:119], v[4:19]
	v_exp_f32_e32 v86, v86
	v_exp_f32_e32 v87, v87
	ds_read_b64_tr_b16 v[116:117], v69 offset:37888
	ds_read_b64_tr_b16 v[118:119], v69 offset:38400
	s_waitcnt lgkmcnt(6)
	v_mfma_f32_32x32x16_bf16 v[4:19], v[152:155], v[76:79], v[4:19]
	v_exp_f32_e32 v88, v88
	v_exp_f32_e32 v89, v89
	ds_read_b64_tr_b16 v[76:77], v69 offset:38912
	ds_read_b64_tr_b16 v[78:79], v69 offset:39424
	s_waitcnt lgkmcnt(6)
	v_mfma_f32_32x32x16_bf16 v[4:19], v[148:151], v[80:83], v[4:19]
	v_exp_f32_e32 v90, v90
	v_exp_f32_e32 v91, v91
	ds_read_b64_tr_b16 v[80:81], v69 offset:39936
	ds_read_b64_tr_b16 v[82:83], v69 offset:40448
	v_add_u32_e32 v69, s24, v230
	ds_read_b128 v[208:211], v69
	ds_read_b128 v[200:203], v69 offset:512
	s_waitcnt lgkmcnt(8)
	v_mfma_f32_32x32x16_bf16 v[20:35], v[160:163], v[72:75], v[20:35]
	v_exp_f32_e32 v92, v92
	v_exp_f32_e32 v93, v93
	ds_read_b128 v[204:207], v69 offset:2048
	ds_read_b128 v[196:199], v69 offset:2560
	s_waitcnt lgkmcnt(8)
	v_mfma_f32_32x32x16_bf16 v[20:35], v[156:159], v[116:119], v[20:35]
	v_exp_f32_e32 v94, v94
	v_exp_f32_e32 v95, v95
	ds_read_b128 v[192:195], v69 offset:4096
	ds_read_b128 v[188:191], v69 offset:4608
	ds_read_b128 v[184:187], v69 offset:6144
	ds_read_b128 v[180:183], v69 offset:6656
	s_waitcnt lgkmcnt(10)
	v_mfma_f32_32x32x16_bf16 v[20:35], v[152:155], v[76:79], v[20:35]
	v_exp_f32_e32 v96, v96
	v_exp_f32_e32 v97, v97
	s_waitcnt lgkmcnt(8)
	v_mfma_f32_32x32x16_bf16 v[20:35], v[148:151], v[80:83], v[20:35]
	v_exp_f32_e32 v98, v98
	v_exp_f32_e32 v99, v99
	s_add_i32 s3, s24, 0x2000
	s_cmpk_lg_i32 s24, 0x4000
	s_cselect_b32 s26, s3, 0
	s_add_i32 s18, s2, 2
	s_add_u32 s14, s14, 0x20000
	s_addc_u32 s15, s15, 0
	s_mov_b32 s17, s16
	s_cmp_ge_u32 s18, s21
	s_waitcnt vmcnt(3) lgkmcnt(0)
	s_barrier
	s_cbranch_scc0 .LBB0_413
	s_add_i32 s64, s2, -3
	s_lshl_b64 s[12:13], s[12:13], 9
	s_add_i32 s2, s64, 1
	s_cmp_lt_u32 s2, s21
	s_cbranch_scc0 .LBB0_441
